# PH6 SwiGLU epilogue de-serialised: the 8 per-row-group ssqX loads issued together at the top (was load + vmcnt(0) per group, each also waiting for the previous group's store); only the last group's wa
# speedup vs baseline: 1.0072x; 1.0072x over previous
; __device__ __forceinline__ void st8(bf16_t* p, f32x4 a, f32x4 b) { u32x4 w; w.x = cvt_pk_bf16(a[0], a[1]); w.y = cvt_pk_bf16(a[2], a[3]); w.z = cvt_pk_bf16(b[0], b[1]); w.w = cvt_pk_bf16(b[2], b[3]); *(u32x4*)p = w; }
;     __device__ __forceinline__ void operator()(const f32x4 (&acc)[2][2][4][2], const Unit& u, int wr, int wc, int fr, int fq) const {
;         asm volatile("" : "+v"(fr), "+v"(fq)); asm volatile("" : "+s"(wr), "+s"(wc));
;         const int rl0 = wr * 64 + fr, pn = u.pn, cw = wc * 32 + fq * 8;
;         bf16_t* base = (u.pm < pm_split) ? ACT1 + (size_t)u.pm * BM * 2816 : ACT2 + (size_t)(u.pm - pm_split) * BM * 2816;
; #pragma unroll
;         for (int ai = 0; ai < 2; ++ai)
; #pragma unroll
;             for (int m = 0; m < 4; ++m) {
;                 const int rl = rl0 + ai * HALF + m * 16;
;                 const float s = rsqrtf(ssqX[u.pm * BM + rl] * (1.0f / 1024.0f) + EPS);
;                 f32x4 o[2];
; #pragma unroll
;                 for (int n = 0; n < 2; ++n) {
;                     const f32x4 g = acc[ai][0][m][n] * s, up = acc[ai][1][m][n] * s;
; #pragma unroll
;                     for (int j = 0; j < 4; ++j) { const float e = __builtin_amdgcn_exp2f(g[j] * -1.4426950408889634f); o[n][j] = g[j] * __builtin_amdgcn_rcpf(1.0f + e) * up[j]; }
;                 }
;                 st8(base + (size_t)rl * 2816 + pn * 128 + cw, o[0], o[1]);
;                 asm volatile("" ::: "memory");
.LBB0_815:
	s_add_i32 s23, s28, 0xffffff76
	s_ashr_i32 s30, s28, 31
	s_cmpk_lt_i32 s28, 0x8a
	s_cselect_b32 s23, s28, s23
	s_cselect_b32 s30, s30, 0
	s_mul_i32 s30, s30, 0x160000
	s_mul_hi_u32 s35, s23, 0x160000
	v_mov_b32_e32 v156, v145
	v_mov_b32_e32 v151, v144
	s_mov_b32 s4, s42
	s_mov_b32 s5, s52
	s_cselect_b32 s31, s49, s7
	s_cselect_b32 s34, s48, s6
	s_add_i32 s35, s35, s30
	s_mul_i32 s23, s23, 0x160000
	s_add_u32 s23, s34, s23
	s_addc_u32 s34, s31, s35
	v_lshl_add_u32 v151, s4, 6, v151
	s_lshl_b32 s4, s28, 8
	v_add_u32_e32 v152, s4, v151
	v_ashrrev_i32_e32 v153, 31, v152
	v_lshl_add_u64 v[152:153], v[152:153], 2, s[14:15]
	global_load_dword v157, v[152:153], off
	global_load_dword v240, v[152:153], off offset:64
	global_load_dword v241, v[152:153], off offset:128
	global_load_dword v242, v[152:153], off offset:192
	global_load_dword v243, v[152:153], off offset:512
	global_load_dword v244, v[152:153], off offset:576
	global_load_dword v245, v[152:153], off offset:640
	global_load_dword v246, v[152:153], off offset:704
	v_mov_b32_e32 v154, v122
	v_mov_b32_e32 v155, v114
	v_mov_b32_e32 v114, v123
	v_mov_b32_e32 v152, v124
	v_mov_b32_e32 v124, v126
	v_mov_b32_e32 v126, v120
	v_lshlrev_b32_e32 v120, 3, v156
	v_mov_b32_e32 v153, v116
	v_mov_b32_e32 v116, v125
	v_mov_b32_e32 v125, v118
	v_mov_b32_e32 v118, v127
	v_mov_b32_e32 v127, v112
	v_mov_b32_e32 v112, v121
	s_lshl_b32 s30, s61, 7
	s_ashr_i32 s31, s30, 31
	s_lshl_b64 s[30:31], s[30:31], 1
	v_lshl_add_u32 v120, s5, 5, v120
	s_add_u32 s30, s23, s30
	v_ashrrev_i32_e32 v121, 31, v120
	s_addc_u32 s31, s34, s31
	v_lshl_add_u64 v[120:121], v[120:121], 1, s[30:31]
	s_waitcnt vmcnt(0)
	v_fmamk_f32 v122, v157, 0x3a800000, v150
	v_mul_f32_e32 v123, 0x4b800000, v122
	v_cmp_gt_f32_e32 vcc, s58, v122
	s_nop 1
	v_cndmask_b32_e32 v122, v122, v123, vcc
	v_rsq_f32_e32 v156, v122
	v_mad_i64_i32 v[122:123], s[30:31], v151, s59, v[120:121]
	v_mul_f32_e32 v157, 0x45800000, v156
	v_cndmask_b32_e32 v156, v156, v157, vcc
	v_pk_mul_f32 v[152:153], v[152:153], v[156:157] op_sel_hi:[1,0]
	v_pk_mul_f32 v[116:117], v[116:117], v[156:157] op_sel_hi:[1,0]
	v_pk_mul_f32 v[124:125], v[124:125], v[156:157] op_sel_hi:[1,0]
	v_pk_mul_f32 v[118:119], v[118:119], v[156:157] op_sel_hi:[1,0]
	v_pk_mul_f32 v[126:127], v[126:127], v[156:157] op_sel_hi:[1,0]
	v_pk_mul_f32 v[112:113], v[112:113], v[156:157] op_sel_hi:[1,0]
	v_pk_mul_f32 v[114:115], v[114:115], v[156:157] op_sel_hi:[1,0]
	v_pk_mul_f32 v[154:155], v[154:155], v[156:157] op_sel_hi:[1,0]
	v_mul_f32_e32 v156, 0xbfb8aa3b, v153
	v_mul_f32_e32 v157, 0xbfb8aa3b, v117
	v_mul_f32_e32 v158, 0xbfb8aa3b, v125
	v_mul_f32_e32 v159, 0xbfb8aa3b, v119
	v_mul_f32_e32 v160, 0xbfb8aa3b, v127
	v_mul_f32_e32 v161, 0xbfb8aa3b, v113
	v_mul_f32_e32 v163, 0xbfb8aa3b, v115
	v_mul_f32_e32 v162, 0xbfb8aa3b, v155
	v_exp_f32_e32 v156, v156
	v_exp_f32_e32 v157, v157
	v_exp_f32_e32 v158, v158
	v_exp_f32_e32 v159, v159
	v_exp_f32_e32 v160, v160
	v_exp_f32_e32 v161, v161
	v_exp_f32_e32 v163, v163
	v_exp_f32_e32 v162, v162
	v_add_f32_e32 v156, 1.0, v156
	v_add_f32_e32 v157, 1.0, v157
	v_add_f32_e32 v158, 1.0, v158
	v_add_f32_e32 v159, 1.0, v159
	v_add_f32_e32 v160, 1.0, v160
	v_add_f32_e32 v161, 1.0, v161
	v_add_f32_e32 v163, 1.0, v163
	v_add_f32_e32 v162, 1.0, v162
	v_rcp_f32_e32 v156, v156
	v_rcp_f32_e32 v157, v157
	v_rcp_f32_e32 v158, v158
	v_rcp_f32_e32 v159, v159
	v_rcp_f32_e32 v160, v160
	v_rcp_f32_e32 v161, v161
	v_rcp_f32_e32 v163, v163
	v_rcp_f32_e32 v162, v162
	v_mul_f32_e32 v153, v153, v156
	v_mul_f32_e32 v117, v117, v157
	v_mul_f32_e32 v125, v125, v158
	v_mul_f32_e32 v119, v119, v159
	v_mul_f32_e32 v127, v127, v160
	v_mul_f32_e32 v113, v113, v161
	v_mul_f32_e32 v115, v115, v163
	v_mul_f32_e32 v155, v155, v162
	v_mul_f32_e32 v152, v152, v153
	v_mul_f32_e32 v116, v116, v117
	v_mul_f32_e32 v117, v124, v125
	v_mul_f32_e32 v118, v118, v119
	v_mul_f32_e32 v119, v126, v127
	v_mul_f32_e32 v124, v112, v113
	v_mul_f32_e32 v115, v114, v115
	v_cvt_pk_bf16_f32 v112, v152, v116
	v_cvt_pk_bf16_f32 v113, v117, v118
	v_cvt_pk_bf16_f32 v114, v119, v124
	v_mul_f32_e32 v125, v154, v155
	v_cvt_pk_bf16_f32 v115, v125, v115
	global_store_dwordx4 v[122:123], v[112:115], off
	v_add_u32_e32 v117, 32, v151
	s_nop 0
	v_add_u32_e32 v114, 16, v151
	v_add_u32_e32 v112, s4, v114
	v_ashrrev_i32_e32 v113, 31, v112
	v_lshl_add_u64 v[112:113], v[112:113], 2, s[14:15]
	s_nop 1
	v_mov_b32_e32 v115, v240
	v_mov_b32_e32 v113, v100
	v_mov_b32_e32 v100, v109
	v_mov_b32_e32 v109, v102
	v_mov_b32_e32 v102, v111
	v_mov_b32_e32 v111, v96
	v_mov_b32_e32 v96, v105
	v_mov_b32_e32 v105, v98
	v_mov_b32_e32 v98, v107
	v_mov_b32_e32 v112, v108
	v_mov_b32_e32 v108, v110
	v_mov_b32_e32 v110, v104
	v_mov_b32_e32 v104, v106
	v_add_u32_e32 v106, s4, v117
	v_ashrrev_i32_e32 v107, 31, v106
	v_lshl_add_u64 v[106:107], v[106:107], 2, s[14:15]
	v_fmamk_f32 v115, v115, 0x3a800000, v150
	v_mul_f32_e32 v116, 0x4b800000, v115
	v_cmp_gt_f32_e32 vcc, s58, v115
	s_nop 1
	v_cndmask_b32_e32 v115, v115, v116, vcc
	v_rsq_f32_e32 v116, v115
	v_mad_i64_i32 v[114:115], s[30:31], v114, s59, v[120:121]
	v_mul_f32_e32 v118, 0x45800000, v116
	v_cndmask_b32_e32 v116, v116, v118, vcc
	v_pk_mul_f32 v[98:99], v[98:99], v[116:117] op_sel_hi:[1,0]
	v_pk_mul_f32 v[112:113], v[112:113], v[116:117] op_sel_hi:[1,0]
	v_pk_mul_f32 v[100:101], v[100:101], v[116:117] op_sel_hi:[1,0]
	v_pk_mul_f32 v[108:109], v[108:109], v[116:117] op_sel_hi:[1,0]
	v_pk_mul_f32 v[102:103], v[102:103], v[116:117] op_sel_hi:[1,0]
	v_pk_mul_f32 v[110:111], v[110:111], v[116:117] op_sel_hi:[1,0]
	v_pk_mul_f32 v[96:97], v[96:97], v[116:117] op_sel_hi:[1,0]
	v_pk_mul_f32 v[104:105], v[104:105], v[116:117] op_sel_hi:[1,0]
; __device__ __forceinline__ void st8(bf16_t* p, f32x4 a, f32x4 b) { u32x4 w; w.x = cvt_pk_bf16(a[0], a[1]); w.y = cvt_pk_bf16(a[2], a[3]); w.z = cvt_pk_bf16(b[0], b[1]); w.w = cvt_pk_bf16(b[2], b[3]); *(u32x4*)p = w; }
;     __device__ __forceinline__ void operator()(const f32x4 (&acc)[2][2][4][2], const Unit& u, int wr, int wc, int fr, int fq) const {
;     ...
;             for (int m = 0; m < 4; ++m) {
;                 const int rl = rl0 + ai * HALF + m * 16;
;                 const float s = rsqrtf(ssqX[u.pm * BM + rl] * (1.0f / 1024.0f) + EPS);
;                 f32x4 o[2];
; #pragma unroll
;                 for (int n = 0; n < 2; ++n) {
;                     const f32x4 g = acc[ai][0][m][n] * s, up = acc[ai][1][m][n] * s;
; #pragma unroll
;                     for (int j = 0; j < 4; ++j) { const float e = __builtin_amdgcn_exp2f(g[j] * -1.4426950408889634f); o[n][j] = g[j] * __builtin_amdgcn_rcpf(1.0f + e) * up[j]; }
;                 }
;                 st8(base + (size_t)rl * 2816 + pn * 128 + cw, o[0], o[1]);
;                 asm volatile("" ::: "memory");
	v_mul_f32_e32 v126, 0xbfb8aa3b, v99
	v_mul_f32_e32 v116, 0xbfb8aa3b, v113
	v_mul_f32_e32 v118, 0xbfb8aa3b, v101
	v_mul_f32_e32 v119, 0xbfb8aa3b, v109
	v_mul_f32_e32 v122, 0xbfb8aa3b, v103
	v_mul_f32_e32 v123, 0xbfb8aa3b, v111
	v_mul_f32_e32 v124, 0xbfb8aa3b, v97
	v_mul_f32_e32 v125, 0xbfb8aa3b, v105
	v_exp_f32_e32 v126, v126
	v_exp_f32_e32 v116, v116
	v_exp_f32_e32 v118, v118
	v_exp_f32_e32 v119, v119
	v_exp_f32_e32 v122, v122
	v_exp_f32_e32 v123, v123
	v_exp_f32_e32 v124, v124
	v_exp_f32_e32 v125, v125
	v_add_f32_e32 v126, 1.0, v126
	v_add_f32_e32 v116, 1.0, v116
	v_add_f32_e32 v118, 1.0, v118
	v_add_f32_e32 v119, 1.0, v119
	v_add_f32_e32 v122, 1.0, v122
	v_add_f32_e32 v123, 1.0, v123
	v_add_f32_e32 v124, 1.0, v124
	v_add_f32_e32 v125, 1.0, v125
	v_rcp_f32_e32 v126, v126
	v_rcp_f32_e32 v116, v116
	v_rcp_f32_e32 v118, v118
	v_rcp_f32_e32 v119, v119
	v_rcp_f32_e32 v122, v122
	v_rcp_f32_e32 v123, v123
	v_rcp_f32_e32 v124, v124
	v_rcp_f32_e32 v125, v125
	v_mul_f32_e32 v99, v99, v126
	v_mul_f32_e32 v113, v113, v116
	v_mul_f32_e32 v101, v101, v118
	v_mul_f32_e32 v109, v109, v119
	v_mul_f32_e32 v103, v103, v122
	v_mul_f32_e32 v111, v111, v123
	v_mul_f32_e32 v97, v97, v124
	v_mul_f32_e32 v105, v105, v125
	v_mul_f32_e32 v99, v98, v99
	v_mul_f32_e32 v112, v112, v113
	v_mul_f32_e32 v100, v100, v101
	v_mul_f32_e32 v101, v108, v109
	v_mul_f32_e32 v102, v102, v103
	v_mul_f32_e32 v103, v110, v111
	v_mul_f32_e32 v108, v96, v97
	v_mul_f32_e32 v104, v104, v105
	v_cvt_pk_bf16_f32 v96, v112, v100
	v_cvt_pk_bf16_f32 v97, v101, v102
	v_cvt_pk_bf16_f32 v98, v103, v108
	v_cvt_pk_bf16_f32 v99, v104, v99
	global_store_dwordx4 v[114:115], v[96:99], off
	s_nop 1
	v_mov_b32_e32 v98, v241
	v_add_u32_e32 v101, 48, v151
	v_mov_b32_e32 v97, v84
	v_mov_b32_e32 v84, v93
	v_mov_b32_e32 v93, v86
	v_mov_b32_e32 v86, v95
	v_mov_b32_e32 v95, v80
	v_mov_b32_e32 v80, v89
	v_mov_b32_e32 v89, v82
	v_mov_b32_e32 v82, v91
	v_mov_b32_e32 v96, v92
	v_mov_b32_e32 v92, v94
	v_mov_b32_e32 v94, v88
	v_mov_b32_e32 v88, v90
	v_add_u32_e32 v90, s4, v101
	v_ashrrev_i32_e32 v91, 31, v90
	v_lshl_add_u64 v[90:91], v[90:91], 2, s[14:15]
	v_fmamk_f32 v98, v98, 0x3a800000, v150
	v_mul_f32_e32 v99, 0x4b800000, v98
	v_cmp_gt_f32_e32 vcc, s58, v98
	s_nop 1
	v_cndmask_b32_e32 v98, v98, v99, vcc
	v_rsq_f32_e32 v100, v98
	v_mad_i64_i32 v[98:99], s[30:31], v117, s59, v[120:121]
	v_mul_f32_e32 v102, 0x45800000, v100
	v_cndmask_b32_e32 v100, v100, v102, vcc
	v_pk_mul_f32 v[82:83], v[82:83], v[100:101] op_sel_hi:[1,0]
	v_pk_mul_f32 v[96:97], v[96:97], v[100:101] op_sel_hi:[1,0]
	v_pk_mul_f32 v[84:85], v[84:85], v[100:101] op_sel_hi:[1,0]
	v_pk_mul_f32 v[92:93], v[92:93], v[100:101] op_sel_hi:[1,0]
	v_pk_mul_f32 v[86:87], v[86:87], v[100:101] op_sel_hi:[1,0]
	v_pk_mul_f32 v[94:95], v[94:95], v[100:101] op_sel_hi:[1,0]
	v_pk_mul_f32 v[80:81], v[80:81], v[100:101] op_sel_hi:[1,0]
	v_pk_mul_f32 v[88:89], v[88:89], v[100:101] op_sel_hi:[1,0]
	v_mul_f32_e32 v108, 0xbfb8aa3b, v83
	v_mul_f32_e32 v100, 0xbfb8aa3b, v97
	v_mul_f32_e32 v102, 0xbfb8aa3b, v85
	v_mul_f32_e32 v103, 0xbfb8aa3b, v93
	v_mul_f32_e32 v104, 0xbfb8aa3b, v87
	v_mul_f32_e32 v105, 0xbfb8aa3b, v95
	v_mul_f32_e32 v106, 0xbfb8aa3b, v81
	v_mul_f32_e32 v107, 0xbfb8aa3b, v89
	v_exp_f32_e32 v108, v108
	v_exp_f32_e32 v100, v100
	v_exp_f32_e32 v102, v102
	v_exp_f32_e32 v103, v103
	v_exp_f32_e32 v104, v104
	v_exp_f32_e32 v105, v105
	v_exp_f32_e32 v106, v106
	v_exp_f32_e32 v107, v107
	v_add_f32_e32 v108, 1.0, v108
	v_add_f32_e32 v100, 1.0, v100
	v_add_f32_e32 v102, 1.0, v102
	v_add_f32_e32 v103, 1.0, v103
	v_add_f32_e32 v104, 1.0, v104
	v_add_f32_e32 v105, 1.0, v105
	v_add_f32_e32 v106, 1.0, v106
	v_add_f32_e32 v107, 1.0, v107
	v_rcp_f32_e32 v108, v108
	v_rcp_f32_e32 v100, v100
	v_rcp_f32_e32 v102, v102
	v_rcp_f32_e32 v103, v103
	v_rcp_f32_e32 v104, v104
	v_rcp_f32_e32 v105, v105
	v_rcp_f32_e32 v106, v106
	v_rcp_f32_e32 v107, v107
	v_mul_f32_e32 v83, v83, v108
	v_mul_f32_e32 v97, v97, v100
	v_mul_f32_e32 v85, v85, v102
	v_mul_f32_e32 v93, v93, v103
	v_mul_f32_e32 v87, v87, v104
	v_mul_f32_e32 v95, v95, v105
	v_mul_f32_e32 v81, v81, v106
	v_mul_f32_e32 v89, v89, v107
	v_mul_f32_e32 v83, v82, v83
	v_mul_f32_e32 v96, v96, v97
	v_mul_f32_e32 v84, v84, v85
	v_mul_f32_e32 v85, v92, v93
	v_mul_f32_e32 v86, v86, v87
	v_mul_f32_e32 v87, v94, v95
	v_mul_f32_e32 v92, v80, v81
	v_mul_f32_e32 v88, v88, v89
	v_cvt_pk_bf16_f32 v80, v96, v84
	v_cvt_pk_bf16_f32 v81, v85, v86
	v_cvt_pk_bf16_f32 v82, v87, v92
	v_cvt_pk_bf16_f32 v83, v88, v83
	global_store_dwordx4 v[98:99], v[80:83], off
	s_nop 1
	v_mov_b32_e32 v82, v242
	v_add_u32_e32 v85, 0x80, v151
	v_mov_b32_e32 v81, v68
	v_mov_b32_e32 v68, v77
	v_mov_b32_e32 v77, v70
	v_mov_b32_e32 v70, v79
	v_mov_b32_e32 v79, v64
	v_mov_b32_e32 v64, v73
	v_mov_b32_e32 v73, v66
	v_mov_b32_e32 v66, v75
	v_mov_b32_e32 v80, v76
	v_mov_b32_e32 v76, v78
	v_mov_b32_e32 v78, v72
	v_mov_b32_e32 v72, v74
	v_add_u32_e32 v74, s4, v85
	v_ashrrev_i32_e32 v75, 31, v74
	v_lshl_add_u64 v[74:75], v[74:75], 2, s[14:15]
	v_fmamk_f32 v82, v82, 0x3a800000, v150
	v_mul_f32_e32 v83, 0x4b800000, v82
	v_cmp_gt_f32_e32 vcc, s58, v82
	s_nop 1
	v_cndmask_b32_e32 v82, v82, v83, vcc
	v_rsq_f32_e32 v84, v82
	v_mad_i64_i32 v[82:83], s[30:31], v101, s59, v[120:121]
	v_mul_f32_e32 v86, 0x45800000, v84
	v_cndmask_b32_e32 v84, v84, v86, vcc
	v_pk_mul_f32 v[66:67], v[66:67], v[84:85] op_sel_hi:[1,0]
	v_pk_mul_f32 v[80:81], v[80:81], v[84:85] op_sel_hi:[1,0]
	v_pk_mul_f32 v[68:69], v[68:69], v[84:85] op_sel_hi:[1,0]
	v_pk_mul_f32 v[76:77], v[76:77], v[84:85] op_sel_hi:[1,0]
	v_pk_mul_f32 v[70:71], v[70:71], v[84:85] op_sel_hi:[1,0]
	v_pk_mul_f32 v[78:79], v[78:79], v[84:85] op_sel_hi:[1,0]
; __device__ __forceinline__ void st8(bf16_t* p, f32x4 a, f32x4 b) { u32x4 w; w.x = cvt_pk_bf16(a[0], a[1]); w.y = cvt_pk_bf16(a[2], a[3]); w.z = cvt_pk_bf16(b[0], b[1]); w.w = cvt_pk_bf16(b[2], b[3]); *(u32x4*)p = w; }
;     __device__ __forceinline__ void operator()(const f32x4 (&acc)[2][2][4][2], const Unit& u, int wr, int wc, int fr, int fq) const {
;     ...
;             for (int m = 0; m < 4; ++m) {
;                 const int rl = rl0 + ai * HALF + m * 16;
;                 const float s = rsqrtf(ssqX[u.pm * BM + rl] * (1.0f / 1024.0f) + EPS);
;                 f32x4 o[2];
; #pragma unroll
;                 for (int n = 0; n < 2; ++n) {
;                     const f32x4 g = acc[ai][0][m][n] * s, up = acc[ai][1][m][n] * s;
; #pragma unroll
;                     for (int j = 0; j < 4; ++j) { const float e = __builtin_amdgcn_exp2f(g[j] * -1.4426950408889634f); o[n][j] = g[j] * __builtin_amdgcn_rcpf(1.0f + e) * up[j]; }
;                 }
;                 st8(base + (size_t)rl * 2816 + pn * 128 + cw, o[0], o[1]);
;                 asm volatile("" ::: "memory");
	v_pk_mul_f32 v[64:65], v[64:65], v[84:85] op_sel_hi:[1,0]
	v_pk_mul_f32 v[72:73], v[72:73], v[84:85] op_sel_hi:[1,0]
	v_mul_f32_e32 v92, 0xbfb8aa3b, v67
	v_mul_f32_e32 v84, 0xbfb8aa3b, v81
	v_mul_f32_e32 v86, 0xbfb8aa3b, v69
	v_mul_f32_e32 v87, 0xbfb8aa3b, v77
	v_mul_f32_e32 v88, 0xbfb8aa3b, v71
	v_mul_f32_e32 v89, 0xbfb8aa3b, v79
	v_mul_f32_e32 v90, 0xbfb8aa3b, v65
	v_mul_f32_e32 v91, 0xbfb8aa3b, v73
	v_exp_f32_e32 v92, v92
	v_exp_f32_e32 v84, v84
	v_exp_f32_e32 v86, v86
	v_exp_f32_e32 v87, v87
	v_exp_f32_e32 v88, v88
	v_exp_f32_e32 v89, v89
	v_exp_f32_e32 v90, v90
	v_exp_f32_e32 v91, v91
	v_add_f32_e32 v92, 1.0, v92
	v_add_f32_e32 v84, 1.0, v84
	v_add_f32_e32 v86, 1.0, v86
	v_add_f32_e32 v87, 1.0, v87
	v_add_f32_e32 v88, 1.0, v88
	v_add_f32_e32 v89, 1.0, v89
	v_add_f32_e32 v90, 1.0, v90
	v_add_f32_e32 v91, 1.0, v91
	v_rcp_f32_e32 v92, v92
	v_rcp_f32_e32 v84, v84
	v_rcp_f32_e32 v86, v86
	v_rcp_f32_e32 v87, v87
	v_rcp_f32_e32 v88, v88
	v_rcp_f32_e32 v89, v89
	v_rcp_f32_e32 v90, v90
	v_rcp_f32_e32 v91, v91
	v_mul_f32_e32 v67, v67, v92
	v_mul_f32_e32 v81, v81, v84
	v_mul_f32_e32 v69, v69, v86
	v_mul_f32_e32 v77, v77, v87
	v_mul_f32_e32 v71, v71, v88
	v_mul_f32_e32 v79, v79, v89
	v_mul_f32_e32 v65, v65, v90
	v_mul_f32_e32 v73, v73, v91
	v_mul_f32_e32 v67, v66, v67
	v_mul_f32_e32 v80, v80, v81
	v_mul_f32_e32 v68, v68, v69
	v_mul_f32_e32 v69, v76, v77
	v_mul_f32_e32 v70, v70, v71
	v_mul_f32_e32 v71, v78, v79
	v_mul_f32_e32 v76, v64, v65
	v_mul_f32_e32 v72, v72, v73
	v_cvt_pk_bf16_f32 v64, v80, v68
	v_cvt_pk_bf16_f32 v65, v69, v70
	v_cvt_pk_bf16_f32 v66, v71, v76
	v_cvt_pk_bf16_f32 v67, v72, v67
	global_store_dwordx4 v[82:83], v[64:67], off
	s_nop 1
	v_mov_b32_e32 v66, v243
	v_add_u32_e32 v69, 0x90, v151
	v_mov_b32_e32 v65, v52
	v_mov_b32_e32 v52, v61
	v_mov_b32_e32 v61, v54
	v_mov_b32_e32 v54, v63
	v_mov_b32_e32 v63, v48
	v_mov_b32_e32 v48, v57
	v_mov_b32_e32 v57, v50
	v_mov_b32_e32 v50, v59
	v_mov_b32_e32 v64, v60
	v_mov_b32_e32 v60, v62
	v_mov_b32_e32 v62, v56
	v_mov_b32_e32 v56, v58
	v_add_u32_e32 v58, s4, v69
	v_ashrrev_i32_e32 v59, 31, v58
	v_lshl_add_u64 v[58:59], v[58:59], 2, s[14:15]
	v_fmamk_f32 v66, v66, 0x3a800000, v150
	v_mul_f32_e32 v67, 0x4b800000, v66
	v_cmp_gt_f32_e32 vcc, s58, v66
	s_nop 1
	v_cndmask_b32_e32 v66, v66, v67, vcc
	v_rsq_f32_e32 v68, v66
	v_mad_i64_i32 v[66:67], s[30:31], v85, s59, v[120:121]
	v_mul_f32_e32 v70, 0x45800000, v68
	v_cndmask_b32_e32 v68, v68, v70, vcc
	v_pk_mul_f32 v[50:51], v[50:51], v[68:69] op_sel_hi:[1,0]
	v_pk_mul_f32 v[64:65], v[64:65], v[68:69] op_sel_hi:[1,0]
	v_pk_mul_f32 v[52:53], v[52:53], v[68:69] op_sel_hi:[1,0]
	v_pk_mul_f32 v[60:61], v[60:61], v[68:69] op_sel_hi:[1,0]
	v_pk_mul_f32 v[54:55], v[54:55], v[68:69] op_sel_hi:[1,0]
	v_pk_mul_f32 v[62:63], v[62:63], v[68:69] op_sel_hi:[1,0]
	v_pk_mul_f32 v[48:49], v[48:49], v[68:69] op_sel_hi:[1,0]
	v_pk_mul_f32 v[56:57], v[56:57], v[68:69] op_sel_hi:[1,0]
	v_mul_f32_e32 v76, 0xbfb8aa3b, v51
	v_mul_f32_e32 v68, 0xbfb8aa3b, v65
	v_mul_f32_e32 v70, 0xbfb8aa3b, v53
	v_mul_f32_e32 v71, 0xbfb8aa3b, v61
	v_mul_f32_e32 v72, 0xbfb8aa3b, v55
	v_mul_f32_e32 v73, 0xbfb8aa3b, v63
	v_mul_f32_e32 v74, 0xbfb8aa3b, v49
	v_mul_f32_e32 v75, 0xbfb8aa3b, v57
	v_exp_f32_e32 v76, v76
	v_exp_f32_e32 v68, v68
	v_exp_f32_e32 v70, v70
	v_exp_f32_e32 v71, v71
	v_exp_f32_e32 v72, v72
	v_exp_f32_e32 v73, v73
	v_exp_f32_e32 v74, v74
	v_exp_f32_e32 v75, v75
	v_add_f32_e32 v76, 1.0, v76
	v_add_f32_e32 v68, 1.0, v68
	v_add_f32_e32 v70, 1.0, v70
	v_add_f32_e32 v71, 1.0, v71
	v_add_f32_e32 v72, 1.0, v72
	v_add_f32_e32 v73, 1.0, v73
	v_add_f32_e32 v74, 1.0, v74
	v_add_f32_e32 v75, 1.0, v75
	v_rcp_f32_e32 v76, v76
	v_rcp_f32_e32 v68, v68
	v_rcp_f32_e32 v70, v70
	v_rcp_f32_e32 v71, v71
	v_rcp_f32_e32 v72, v72
	v_rcp_f32_e32 v73, v73
	v_rcp_f32_e32 v74, v74
	v_rcp_f32_e32 v75, v75
	v_mul_f32_e32 v51, v51, v76
	v_mul_f32_e32 v65, v65, v68
	v_mul_f32_e32 v53, v53, v70
	v_mul_f32_e32 v61, v61, v71
	v_mul_f32_e32 v55, v55, v72
	v_mul_f32_e32 v63, v63, v73
	v_mul_f32_e32 v49, v49, v74
	v_mul_f32_e32 v57, v57, v75
	v_mul_f32_e32 v51, v50, v51
	v_mul_f32_e32 v64, v64, v65
	v_mul_f32_e32 v52, v52, v53
	v_mul_f32_e32 v53, v60, v61
	v_mul_f32_e32 v54, v54, v55
	v_mul_f32_e32 v55, v62, v63
	v_mul_f32_e32 v60, v48, v49
	v_mul_f32_e32 v56, v56, v57
	v_cvt_pk_bf16_f32 v48, v64, v52
	v_cvt_pk_bf16_f32 v49, v53, v54
	v_cvt_pk_bf16_f32 v50, v55, v60
	v_cvt_pk_bf16_f32 v51, v56, v51
	global_store_dwordx4 v[66:67], v[48:51], off
	s_nop 1
	v_mov_b32_e32 v50, v244
	v_add_u32_e32 v53, 0xa0, v151
	v_mov_b32_e32 v49, v36
	v_mov_b32_e32 v36, v45
	v_mov_b32_e32 v45, v38
	v_mov_b32_e32 v38, v47
	v_mov_b32_e32 v47, v32
	v_mov_b32_e32 v32, v41
	v_mov_b32_e32 v41, v34
	v_mov_b32_e32 v34, v43
	v_mov_b32_e32 v48, v44
	v_mov_b32_e32 v44, v46
	v_mov_b32_e32 v46, v40
	v_mov_b32_e32 v40, v42
	v_add_u32_e32 v42, s4, v53
	v_ashrrev_i32_e32 v43, 31, v42
	v_lshl_add_u64 v[42:43], v[42:43], 2, s[14:15]
	v_fmamk_f32 v50, v50, 0x3a800000, v150
	v_mul_f32_e32 v51, 0x4b800000, v50
	v_cmp_gt_f32_e32 vcc, s58, v50
	s_nop 1
	v_cndmask_b32_e32 v50, v50, v51, vcc
	v_rsq_f32_e32 v52, v50
	v_mad_i64_i32 v[50:51], s[30:31], v69, s59, v[120:121]
	v_mul_f32_e32 v54, 0x45800000, v52
	v_cndmask_b32_e32 v52, v52, v54, vcc
	v_pk_mul_f32 v[34:35], v[34:35], v[52:53] op_sel_hi:[1,0]
	v_pk_mul_f32 v[48:49], v[48:49], v[52:53] op_sel_hi:[1,0]
	v_pk_mul_f32 v[36:37], v[36:37], v[52:53] op_sel_hi:[1,0]
	v_pk_mul_f32 v[44:45], v[44:45], v[52:53] op_sel_hi:[1,0]
	v_pk_mul_f32 v[38:39], v[38:39], v[52:53] op_sel_hi:[1,0]
	v_pk_mul_f32 v[46:47], v[46:47], v[52:53] op_sel_hi:[1,0]
	v_pk_mul_f32 v[32:33], v[32:33], v[52:53] op_sel_hi:[1,0]
; __device__ __forceinline__ void st8(bf16_t* p, f32x4 a, f32x4 b) { u32x4 w; w.x = cvt_pk_bf16(a[0], a[1]); w.y = cvt_pk_bf16(a[2], a[3]); w.z = cvt_pk_bf16(b[0], b[1]); w.w = cvt_pk_bf16(b[2], b[3]); *(u32x4*)p = w; }
;     __device__ __forceinline__ void operator()(const f32x4 (&acc)[2][2][4][2], const Unit& u, int wr, int wc, int fr, int fq) const {
;     ...
;             for (int m = 0; m < 4; ++m) {
;                 const int rl = rl0 + ai * HALF + m * 16;
;                 const float s = rsqrtf(ssqX[u.pm * BM + rl] * (1.0f / 1024.0f) + EPS);
;                 f32x4 o[2];
; #pragma unroll
;                 for (int n = 0; n < 2; ++n) {
;                     const f32x4 g = acc[ai][0][m][n] * s, up = acc[ai][1][m][n] * s;
; #pragma unroll
;                     for (int j = 0; j < 4; ++j) { const float e = __builtin_amdgcn_exp2f(g[j] * -1.4426950408889634f); o[n][j] = g[j] * __builtin_amdgcn_rcpf(1.0f + e) * up[j]; }
;                 }
;                 st8(base + (size_t)rl * 2816 + pn * 128 + cw, o[0], o[1]);
;                 asm volatile("" ::: "memory");
	v_pk_mul_f32 v[40:41], v[40:41], v[52:53] op_sel_hi:[1,0]
	v_mul_f32_e32 v60, 0xbfb8aa3b, v35
	v_mul_f32_e32 v52, 0xbfb8aa3b, v49
	v_mul_f32_e32 v54, 0xbfb8aa3b, v37
	v_mul_f32_e32 v55, 0xbfb8aa3b, v45
	v_mul_f32_e32 v56, 0xbfb8aa3b, v39
	v_mul_f32_e32 v57, 0xbfb8aa3b, v47
	v_mul_f32_e32 v58, 0xbfb8aa3b, v33
	v_mul_f32_e32 v59, 0xbfb8aa3b, v41
	v_exp_f32_e32 v60, v60
	v_exp_f32_e32 v52, v52
	v_exp_f32_e32 v54, v54
	v_exp_f32_e32 v55, v55
	v_exp_f32_e32 v56, v56
	v_exp_f32_e32 v57, v57
	v_exp_f32_e32 v58, v58
	v_exp_f32_e32 v59, v59
	v_add_f32_e32 v60, 1.0, v60
	v_add_f32_e32 v52, 1.0, v52
	v_add_f32_e32 v54, 1.0, v54
	v_add_f32_e32 v55, 1.0, v55
	v_add_f32_e32 v56, 1.0, v56
	v_add_f32_e32 v57, 1.0, v57
	v_add_f32_e32 v58, 1.0, v58
	v_add_f32_e32 v59, 1.0, v59
	v_rcp_f32_e32 v60, v60
	v_rcp_f32_e32 v52, v52
	v_rcp_f32_e32 v54, v54
	v_rcp_f32_e32 v55, v55
	v_rcp_f32_e32 v56, v56
	v_rcp_f32_e32 v57, v57
	v_rcp_f32_e32 v58, v58
	v_rcp_f32_e32 v59, v59
	v_mul_f32_e32 v35, v35, v60
	v_mul_f32_e32 v49, v49, v52
	v_mul_f32_e32 v37, v37, v54
	v_mul_f32_e32 v45, v45, v55
	v_mul_f32_e32 v39, v39, v56
	v_mul_f32_e32 v47, v47, v57
	v_mul_f32_e32 v33, v33, v58
	v_mul_f32_e32 v41, v41, v59
	v_mul_f32_e32 v35, v34, v35
	v_mul_f32_e32 v48, v48, v49
	v_mul_f32_e32 v36, v36, v37
	v_mul_f32_e32 v37, v44, v45
	v_mul_f32_e32 v38, v38, v39
	v_mul_f32_e32 v39, v46, v47
	v_mul_f32_e32 v44, v32, v33
	v_mul_f32_e32 v40, v40, v41
	v_cvt_pk_bf16_f32 v32, v48, v36
	v_cvt_pk_bf16_f32 v33, v37, v38
	v_cvt_pk_bf16_f32 v34, v39, v44
	v_cvt_pk_bf16_f32 v35, v40, v35
	global_store_dwordx4 v[50:51], v[32:35], off
	s_nop 1
	v_mov_b32_e32 v34, v245
	v_add_u32_e32 v37, 0xb0, v151
	v_mov_b32_e32 v33, v20
	v_mov_b32_e32 v20, v29
	v_mov_b32_e32 v29, v22
	v_mov_b32_e32 v22, v31
	v_mov_b32_e32 v31, v16
	v_mov_b32_e32 v16, v25
	v_mov_b32_e32 v25, v18
	v_mov_b32_e32 v18, v27
	v_mov_b32_e32 v32, v28
	v_mov_b32_e32 v28, v30
	v_mov_b32_e32 v30, v24
	v_mov_b32_e32 v24, v26
	v_add_u32_e32 v26, s4, v37
	v_ashrrev_i32_e32 v27, 31, v26
	v_lshl_add_u64 v[26:27], v[26:27], 2, s[14:15]
	v_fmamk_f32 v34, v34, 0x3a800000, v150
	v_mul_f32_e32 v35, 0x4b800000, v34
	v_cmp_gt_f32_e32 vcc, s58, v34
	s_nop 1
	v_cndmask_b32_e32 v34, v34, v35, vcc
	v_rsq_f32_e32 v36, v34
	v_mad_i64_i32 v[34:35], s[4:5], v53, s59, v[120:121]
	v_mul_f32_e32 v38, 0x45800000, v36
	v_cndmask_b32_e32 v36, v36, v38, vcc
	v_pk_mul_f32 v[18:19], v[18:19], v[36:37] op_sel_hi:[1,0]
	v_pk_mul_f32 v[32:33], v[32:33], v[36:37] op_sel_hi:[1,0]
	v_pk_mul_f32 v[20:21], v[20:21], v[36:37] op_sel_hi:[1,0]
	v_pk_mul_f32 v[28:29], v[28:29], v[36:37] op_sel_hi:[1,0]
	v_pk_mul_f32 v[22:23], v[22:23], v[36:37] op_sel_hi:[1,0]
	v_pk_mul_f32 v[30:31], v[30:31], v[36:37] op_sel_hi:[1,0]
	v_pk_mul_f32 v[16:17], v[16:17], v[36:37] op_sel_hi:[1,0]
	v_pk_mul_f32 v[24:25], v[24:25], v[36:37] op_sel_hi:[1,0]
	v_mul_f32_e32 v44, 0xbfb8aa3b, v19
	v_mul_f32_e32 v36, 0xbfb8aa3b, v33
	v_mul_f32_e32 v38, 0xbfb8aa3b, v21
	v_mul_f32_e32 v39, 0xbfb8aa3b, v29
	v_mul_f32_e32 v40, 0xbfb8aa3b, v23
	v_mul_f32_e32 v41, 0xbfb8aa3b, v31
	v_mul_f32_e32 v42, 0xbfb8aa3b, v17
	v_mul_f32_e32 v43, 0xbfb8aa3b, v25
	v_exp_f32_e32 v44, v44
	v_exp_f32_e32 v36, v36
	v_exp_f32_e32 v38, v38
	v_exp_f32_e32 v39, v39
	v_exp_f32_e32 v40, v40
	v_exp_f32_e32 v41, v41
	v_exp_f32_e32 v42, v42
	v_exp_f32_e32 v43, v43
	v_add_f32_e32 v44, 1.0, v44
	v_add_f32_e32 v36, 1.0, v36
	v_add_f32_e32 v38, 1.0, v38
	v_add_f32_e32 v39, 1.0, v39
	v_add_f32_e32 v40, 1.0, v40
	v_add_f32_e32 v41, 1.0, v41
	v_add_f32_e32 v42, 1.0, v42
	v_add_f32_e32 v43, 1.0, v43
	v_rcp_f32_e32 v44, v44
	v_rcp_f32_e32 v36, v36
	v_rcp_f32_e32 v38, v38
	v_rcp_f32_e32 v39, v39
	v_rcp_f32_e32 v40, v40
	v_rcp_f32_e32 v41, v41
	v_rcp_f32_e32 v42, v42
	v_rcp_f32_e32 v43, v43
	v_mul_f32_e32 v19, v19, v44
	v_mul_f32_e32 v33, v33, v36
	v_mul_f32_e32 v21, v21, v38
	v_mul_f32_e32 v29, v29, v39
	v_mul_f32_e32 v23, v23, v40
	v_mul_f32_e32 v31, v31, v41
	v_mul_f32_e32 v17, v17, v42
	v_mul_f32_e32 v25, v25, v43
	v_mul_f32_e32 v19, v18, v19
	v_mul_f32_e32 v32, v32, v33
	v_mul_f32_e32 v20, v20, v21
	v_mul_f32_e32 v21, v28, v29
	v_mul_f32_e32 v22, v22, v23
	v_mul_f32_e32 v23, v30, v31
	v_mul_f32_e32 v28, v16, v17
	v_mul_f32_e32 v24, v24, v25
	v_cvt_pk_bf16_f32 v16, v32, v20
	v_cvt_pk_bf16_f32 v17, v21, v22
	v_cvt_pk_bf16_f32 v18, v23, v28
	v_cvt_pk_bf16_f32 v19, v24, v19
	global_store_dwordx4 v[34:35], v[16:19], off
	s_nop 1
	v_mov_b32_e32 v18, v246
	s_nop 0
	v_mov_b32_e32 v17, v4
	v_mov_b32_e32 v4, v13
	v_mov_b32_e32 v13, v6
	v_mov_b32_e32 v6, v15
	v_mov_b32_e32 v15, v0
	v_mov_b32_e32 v0, v9
	v_mov_b32_e32 v9, v2
	v_mov_b32_e32 v16, v12
	v_mov_b32_e32 v12, v14
	v_mov_b32_e32 v14, v8
	v_mov_b32_e32 v8, v10
	s_waitcnt vmcnt(0)
; __device__ __forceinline__ void st8(bf16_t* p, f32x4 a, f32x4 b) { u32x4 w; w.x = cvt_pk_bf16(a[0], a[1]); w.y = cvt_pk_bf16(a[2], a[3]); w.z = cvt_pk_bf16(b[0], b[1]); w.w = cvt_pk_bf16(b[2], b[3]); *(u32x4*)p = w; }
; #define PG8_BAR __builtin_amdgcn_s_barrier()
;     __device__ __forceinline__ void operator()(const f32x4 (&acc)[2][2][4][2], const Unit& u, int wr, int wc, int fr, int fq) const {
;     ...
;                 const int rl = rl0 + ai * HALF + m * 16;
;                 const float s = rsqrtf(ssqX[u.pm * BM + rl] * (1.0f / 1024.0f) + EPS);
;                 f32x4 o[2];
; #pragma unroll
;                 for (int n = 0; n < 2; ++n) {
;                     const f32x4 g = acc[ai][0][m][n] * s, up = acc[ai][1][m][n] * s;
; #pragma unroll
;                     for (int j = 0; j < 4; ++j) { const float e = __builtin_amdgcn_exp2f(g[j] * -1.4426950408889634f); o[n][j] = g[j] * __builtin_amdgcn_rcpf(1.0f + e) * up[j]; }
;                 }
;                 st8(base + (size_t)rl * 2816 + pn * 128 + cw, o[0], o[1]);
;                 asm volatile("" ::: "memory");
;             }
; template <class Epi, class Sched, bool ALIGN_EPI = false, bool SP2 = false>
; __device__ __forceinline__ void gemm_phase(PG8_LAS unsigned char* lds, const Gemm g, const Sched& S, const Epi& E) {
;     ...
;         cur = nxt; cA = nA; cB = nB; ++ui;
;         if constexpr (ALIGN_EPI) { if (wr == 1) PG8_BAR; }
	v_fmamk_f32 v2, v18, 0x3a800000, v150
	v_mul_f32_e32 v10, 0x4b800000, v2
	v_cmp_gt_f32_e32 vcc, s58, v2
	s_nop 1
	v_cndmask_b32_e32 v2, v2, v10, vcc
	v_rsq_f32_e32 v18, v2
	v_mov_b32_e32 v2, v11
	v_mad_i64_i32 v[10:11], s[4:5], v37, s59, v[120:121]
	v_mul_f32_e32 v19, 0x45800000, v18
	v_cndmask_b32_e32 v18, v18, v19, vcc
	v_pk_mul_f32 v[2:3], v[2:3], v[18:19] op_sel_hi:[1,0]
	v_pk_mul_f32 v[16:17], v[16:17], v[18:19] op_sel_hi:[1,0]
	v_pk_mul_f32 v[4:5], v[4:5], v[18:19] op_sel_hi:[1,0]
	v_pk_mul_f32 v[12:13], v[12:13], v[18:19] op_sel_hi:[1,0]
	v_pk_mul_f32 v[6:7], v[6:7], v[18:19] op_sel_hi:[1,0]
	v_pk_mul_f32 v[14:15], v[14:15], v[18:19] op_sel_hi:[1,0]
	v_pk_mul_f32 v[0:1], v[0:1], v[18:19] op_sel_hi:[1,0]
	v_pk_mul_f32 v[8:9], v[8:9], v[18:19] op_sel_hi:[1,0]
	v_mul_f32_e32 v25, 0xbfb8aa3b, v3
	v_mul_f32_e32 v18, 0xbfb8aa3b, v17
	v_mul_f32_e32 v19, 0xbfb8aa3b, v5
	v_mul_f32_e32 v20, 0xbfb8aa3b, v13
	v_mul_f32_e32 v21, 0xbfb8aa3b, v7
	v_mul_f32_e32 v22, 0xbfb8aa3b, v15
	v_mul_f32_e32 v23, 0xbfb8aa3b, v1
	v_mul_f32_e32 v24, 0xbfb8aa3b, v9
	v_exp_f32_e32 v25, v25
	v_exp_f32_e32 v18, v18
	v_exp_f32_e32 v19, v19
	v_exp_f32_e32 v20, v20
	v_exp_f32_e32 v21, v21
	v_exp_f32_e32 v22, v22
	v_exp_f32_e32 v23, v23
	v_exp_f32_e32 v24, v24
	v_add_f32_e32 v25, 1.0, v25
	v_add_f32_e32 v18, 1.0, v18
	v_add_f32_e32 v19, 1.0, v19
	v_add_f32_e32 v20, 1.0, v20
	v_add_f32_e32 v21, 1.0, v21
	v_add_f32_e32 v22, 1.0, v22
	v_add_f32_e32 v23, 1.0, v23
	v_add_f32_e32 v24, 1.0, v24
	v_rcp_f32_e32 v25, v25
	v_rcp_f32_e32 v18, v18
	v_rcp_f32_e32 v19, v19
	v_rcp_f32_e32 v20, v20
	v_rcp_f32_e32 v21, v21
	v_rcp_f32_e32 v22, v22
	v_rcp_f32_e32 v23, v23
	v_rcp_f32_e32 v24, v24
	v_mul_f32_e32 v3, v3, v25
	v_mul_f32_e32 v17, v17, v18
	v_mul_f32_e32 v5, v5, v19
	v_mul_f32_e32 v13, v13, v20
	v_mul_f32_e32 v7, v7, v21
	v_mul_f32_e32 v15, v15, v22
	v_mul_f32_e32 v1, v1, v23
	v_mul_f32_e32 v9, v9, v24
	v_mul_f32_e32 v3, v2, v3
	v_mul_f32_e32 v16, v16, v17
	v_mul_f32_e32 v4, v4, v5
	v_mul_f32_e32 v5, v12, v13
	v_mul_f32_e32 v6, v6, v7
	v_mul_f32_e32 v7, v14, v15
	v_mul_f32_e32 v12, v0, v1
	v_mul_f32_e32 v8, v8, v9
	v_cvt_pk_bf16_f32 v0, v16, v4
	v_cvt_pk_bf16_f32 v1, v5, v6
	v_cvt_pk_bf16_f32 v2, v7, v12
	v_cvt_pk_bf16_f32 v3, v8, v3
	global_store_dwordx4 v[10:11], v[0:3], off
	s_and_b64 vcc, exec, s[2:3]
	s_mov_b64 s[2:3], -1
	s_cbranch_vccnz .LBB0_801
	s_andn2_b64 vcc, exec, s[12:13]
	s_cbranch_vccnz .LBB0_800
	s_barrier
	s_branch .LBB0_800

; __device__ __forceinline__ void st8(bf16_t* p, f32x4 a, f32x4 b) { u32x4 w; w.x = cvt_pk_bf16(a[0], a[1]); w.y = cvt_pk_bf16(a[2], a[3]); w.z = cvt_pk_bf16(b[0], b[1]); w.w = cvt_pk_bf16(b[2], b[3]); *(u32x4*)p = w; }
;     __device__ __forceinline__ void operator()(const f32x4 (&acc)[2][2][4][2], const Unit& u, int wr, int wc, int fr, int fq) const {
;         asm volatile("" : "+v"(fr), "+v"(fq)); asm volatile("" : "+s"(wr), "+s"(wc));
;         const int rl0 = wr * 64 + fr, pn = u.pn, cw = wc * 32 + fq * 8;
;         bf16_t* base = (u.pm < pm_split) ? ACT1 + (size_t)u.pm * BM * 2816 : ACT2 + (size_t)(u.pm - pm_split) * BM * 2816;
; #pragma unroll
;         for (int ai = 0; ai < 2; ++ai)
; #pragma unroll
;             for (int m = 0; m < 4; ++m) {
;                 const int rl = rl0 + ai * HALF + m * 16;
;                 const float s = rsqrtf(ssqX[u.pm * BM + rl] * (1.0f / 1024.0f) + EPS);
;                 f32x4 o[2];
; #pragma unroll
;                 for (int n = 0; n < 2; ++n) {
;                     const f32x4 g = acc[ai][0][m][n] * s, up = acc[ai][1][m][n] * s;
; #pragma unroll
;                     for (int j = 0; j < 4; ++j) { const float e = __builtin_amdgcn_exp2f(g[j] * -1.4426950408889634f); o[n][j] = g[j] * __builtin_amdgcn_rcpf(1.0f + e) * up[j]; }
;                 }
;                 st8(base + (size_t)rl * 2816 + pn * 128 + cw, o[0], o[1]);
;                 asm volatile("" ::: "memory");
.LBB0_1615:
	s_add_i32 s23, s28, 0xffffff76
	s_ashr_i32 s30, s28, 31
	s_cmpk_lt_i32 s28, 0x8a
	s_cselect_b32 s23, s28, s23
	s_cselect_b32 s30, s30, 0
	s_mul_i32 s30, s30, 0x160000
	s_mul_hi_u32 s35, s23, 0x160000
	v_mov_b32_e32 v151, v144
	v_mov_b32_e32 v156, v145
	s_mov_b32 s5, s52
	s_mov_b32 s4, s42
	s_cselect_b32 s31, s49, s7
	s_cselect_b32 s34, s48, s6
	s_sub_u32 s84, s92, 0xa140000
	s_subb_u32 s85, s93, 0
	s_cmpk_gt_i32 s28, 0xff
	s_cselect_b32 s34, s84, s34
	s_cselect_b32 s31, s85, s31
	s_add_i32 s35, s35, s30
	s_mul_i32 s23, s23, 0x160000
	s_add_u32 s23, s34, s23
	s_addc_u32 s34, s31, s35
	v_lshl_add_u32 v151, s4, 6, v151
	s_lshl_b32 s4, s28, 8
	v_add_u32_e32 v152, s4, v151
	v_ashrrev_i32_e32 v153, 31, v152
	v_lshl_add_u64 v[152:153], v[152:153], 2, s[14:15]
	global_load_dword v157, v[152:153], off
	global_load_dword v240, v[152:153], off offset:64
	global_load_dword v241, v[152:153], off offset:128
	global_load_dword v242, v[152:153], off offset:192
	global_load_dword v243, v[152:153], off offset:512
	global_load_dword v244, v[152:153], off offset:576
	global_load_dword v245, v[152:153], off offset:640
	global_load_dword v246, v[152:153], off offset:704
	v_mov_b32_e32 v154, v122
	v_mov_b32_e32 v155, v114
	v_mov_b32_e32 v114, v123
	v_mov_b32_e32 v152, v124
	v_mov_b32_e32 v124, v126
	v_mov_b32_e32 v126, v120
	v_lshlrev_b32_e32 v120, 3, v156
	v_mov_b32_e32 v153, v116
	v_mov_b32_e32 v116, v125
	v_mov_b32_e32 v125, v118
	v_mov_b32_e32 v118, v127
	v_mov_b32_e32 v127, v112
	v_mov_b32_e32 v112, v121
	s_lshl_b32 s30, s61, 7
	s_ashr_i32 s31, s30, 31
	s_lshl_b64 s[30:31], s[30:31], 1
	v_lshl_add_u32 v120, s5, 5, v120
	s_add_u32 s30, s23, s30
	v_ashrrev_i32_e32 v121, 31, v120
	s_addc_u32 s31, s34, s31
	v_lshl_add_u64 v[120:121], v[120:121], 1, s[30:31]
	s_waitcnt vmcnt(0)
	v_fmamk_f32 v122, v157, 0x3a800000, v150
	v_mul_f32_e32 v123, 0x4b800000, v122
	v_cmp_gt_f32_e32 vcc, s58, v122
	s_nop 1
	v_cndmask_b32_e32 v122, v122, v123, vcc
	v_rsq_f32_e32 v156, v122
	v_mad_i64_i32 v[122:123], s[30:31], v151, s59, v[120:121]
	v_mul_f32_e32 v157, 0x45800000, v156
	v_cndmask_b32_e32 v156, v156, v157, vcc
	v_pk_mul_f32 v[152:153], v[152:153], v[156:157] op_sel_hi:[1,0]
	v_pk_mul_f32 v[116:117], v[116:117], v[156:157] op_sel_hi:[1,0]
	v_pk_mul_f32 v[124:125], v[124:125], v[156:157] op_sel_hi:[1,0]
	v_pk_mul_f32 v[118:119], v[118:119], v[156:157] op_sel_hi:[1,0]
	v_pk_mul_f32 v[126:127], v[126:127], v[156:157] op_sel_hi:[1,0]
	v_pk_mul_f32 v[112:113], v[112:113], v[156:157] op_sel_hi:[1,0]
	v_pk_mul_f32 v[114:115], v[114:115], v[156:157] op_sel_hi:[1,0]
	v_pk_mul_f32 v[154:155], v[154:155], v[156:157] op_sel_hi:[1,0]
	v_mul_f32_e32 v156, 0xbfb8aa3b, v153
	v_mul_f32_e32 v157, 0xbfb8aa3b, v117
	v_mul_f32_e32 v158, 0xbfb8aa3b, v125
	v_mul_f32_e32 v159, 0xbfb8aa3b, v119
	v_mul_f32_e32 v160, 0xbfb8aa3b, v127
	v_mul_f32_e32 v161, 0xbfb8aa3b, v113
	v_mul_f32_e32 v163, 0xbfb8aa3b, v115
	v_mul_f32_e32 v162, 0xbfb8aa3b, v155
	v_exp_f32_e32 v156, v156
	v_exp_f32_e32 v157, v157
	v_exp_f32_e32 v158, v158
	v_exp_f32_e32 v159, v159
	v_exp_f32_e32 v160, v160
	v_exp_f32_e32 v161, v161
	v_exp_f32_e32 v163, v163
	v_exp_f32_e32 v162, v162
	v_add_f32_e32 v156, 1.0, v156
	v_add_f32_e32 v157, 1.0, v157
	v_add_f32_e32 v158, 1.0, v158
	v_add_f32_e32 v159, 1.0, v159
	v_add_f32_e32 v160, 1.0, v160
	v_add_f32_e32 v161, 1.0, v161
	v_add_f32_e32 v163, 1.0, v163
	v_add_f32_e32 v162, 1.0, v162
	v_rcp_f32_e32 v156, v156
	v_rcp_f32_e32 v157, v157
	v_rcp_f32_e32 v158, v158
	v_rcp_f32_e32 v159, v159
	v_rcp_f32_e32 v160, v160
	v_rcp_f32_e32 v161, v161
	v_rcp_f32_e32 v163, v163
	v_rcp_f32_e32 v162, v162
	v_mul_f32_e32 v153, v153, v156
	v_mul_f32_e32 v117, v117, v157
	v_mul_f32_e32 v125, v125, v158
	v_mul_f32_e32 v119, v119, v159
	v_mul_f32_e32 v127, v127, v160
	v_mul_f32_e32 v113, v113, v161
	v_mul_f32_e32 v115, v115, v163
	v_mul_f32_e32 v155, v155, v162
	v_mul_f32_e32 v152, v152, v153
	v_mul_f32_e32 v116, v116, v117
	v_mul_f32_e32 v117, v124, v125
	v_mul_f32_e32 v118, v118, v119
	v_mul_f32_e32 v119, v126, v127
	v_mul_f32_e32 v124, v112, v113
	v_mul_f32_e32 v115, v114, v115
	v_cvt_pk_bf16_f32 v112, v152, v116
	v_cvt_pk_bf16_f32 v113, v117, v118
	v_cvt_pk_bf16_f32 v114, v119, v124
	v_mul_f32_e32 v125, v154, v155
	v_cvt_pk_bf16_f32 v115, v125, v115
	global_store_dwordx4 v[122:123], v[112:115], off
	v_add_u32_e32 v117, 32, v151
	s_nop 0
	v_add_u32_e32 v114, 16, v151
	v_add_u32_e32 v112, s4, v114
	v_ashrrev_i32_e32 v113, 31, v112
	v_lshl_add_u64 v[112:113], v[112:113], 2, s[14:15]
	s_nop 1
	v_mov_b32_e32 v115, v240
	v_mov_b32_e32 v113, v100
	v_mov_b32_e32 v100, v109
	v_mov_b32_e32 v109, v102
	v_mov_b32_e32 v102, v111
	v_mov_b32_e32 v111, v96
	v_mov_b32_e32 v96, v105
	v_mov_b32_e32 v105, v98
	v_mov_b32_e32 v98, v107
	v_mov_b32_e32 v112, v108
	v_mov_b32_e32 v108, v110
	v_mov_b32_e32 v110, v104
	v_mov_b32_e32 v104, v106
	v_add_u32_e32 v106, s4, v117
	v_ashrrev_i32_e32 v107, 31, v106
	v_lshl_add_u64 v[106:107], v[106:107], 2, s[14:15]
	v_fmamk_f32 v115, v115, 0x3a800000, v150
	v_mul_f32_e32 v116, 0x4b800000, v115
	v_cmp_gt_f32_e32 vcc, s58, v115
	s_nop 1
	v_cndmask_b32_e32 v115, v115, v116, vcc
	v_rsq_f32_e32 v116, v115
	v_mad_i64_i32 v[114:115], s[30:31], v114, s59, v[120:121]
	v_mul_f32_e32 v118, 0x45800000, v116
	v_cndmask_b32_e32 v116, v116, v118, vcc
	v_pk_mul_f32 v[98:99], v[98:99], v[116:117] op_sel_hi:[1,0]
	v_pk_mul_f32 v[112:113], v[112:113], v[116:117] op_sel_hi:[1,0]
	v_pk_mul_f32 v[100:101], v[100:101], v[116:117] op_sel_hi:[1,0]
	v_pk_mul_f32 v[108:109], v[108:109], v[116:117] op_sel_hi:[1,0]
	v_pk_mul_f32 v[102:103], v[102:103], v[116:117] op_sel_hi:[1,0]
; __device__ __forceinline__ void st8(bf16_t* p, f32x4 a, f32x4 b) { u32x4 w; w.x = cvt_pk_bf16(a[0], a[1]); w.y = cvt_pk_bf16(a[2], a[3]); w.z = cvt_pk_bf16(b[0], b[1]); w.w = cvt_pk_bf16(b[2], b[3]); *(u32x4*)p = w; }
;     __device__ __forceinline__ void operator()(const f32x4 (&acc)[2][2][4][2], const Unit& u, int wr, int wc, int fr, int fq) const {
;     ...
;                 const int rl = rl0 + ai * HALF + m * 16;
;                 const float s = rsqrtf(ssqX[u.pm * BM + rl] * (1.0f / 1024.0f) + EPS);
;                 f32x4 o[2];
; #pragma unroll
;                 for (int n = 0; n < 2; ++n) {
;                     const f32x4 g = acc[ai][0][m][n] * s, up = acc[ai][1][m][n] * s;
; #pragma unroll
;                     for (int j = 0; j < 4; ++j) { const float e = __builtin_amdgcn_exp2f(g[j] * -1.4426950408889634f); o[n][j] = g[j] * __builtin_amdgcn_rcpf(1.0f + e) * up[j]; }
;                 }
;                 st8(base + (size_t)rl * 2816 + pn * 128 + cw, o[0], o[1]);
;                 asm volatile("" ::: "memory");
	v_pk_mul_f32 v[110:111], v[110:111], v[116:117] op_sel_hi:[1,0]
	v_pk_mul_f32 v[96:97], v[96:97], v[116:117] op_sel_hi:[1,0]
	v_pk_mul_f32 v[104:105], v[104:105], v[116:117] op_sel_hi:[1,0]
	v_mul_f32_e32 v126, 0xbfb8aa3b, v99
	v_mul_f32_e32 v116, 0xbfb8aa3b, v113
	v_mul_f32_e32 v118, 0xbfb8aa3b, v101
	v_mul_f32_e32 v119, 0xbfb8aa3b, v109
	v_mul_f32_e32 v122, 0xbfb8aa3b, v103
	v_mul_f32_e32 v123, 0xbfb8aa3b, v111
	v_mul_f32_e32 v124, 0xbfb8aa3b, v97
	v_mul_f32_e32 v125, 0xbfb8aa3b, v105
	v_exp_f32_e32 v126, v126
	v_exp_f32_e32 v116, v116
	v_exp_f32_e32 v118, v118
	v_exp_f32_e32 v119, v119
	v_exp_f32_e32 v122, v122
	v_exp_f32_e32 v123, v123
	v_exp_f32_e32 v124, v124
	v_exp_f32_e32 v125, v125
	v_add_f32_e32 v126, 1.0, v126
	v_add_f32_e32 v116, 1.0, v116
	v_add_f32_e32 v118, 1.0, v118
	v_add_f32_e32 v119, 1.0, v119
	v_add_f32_e32 v122, 1.0, v122
	v_add_f32_e32 v123, 1.0, v123
	v_add_f32_e32 v124, 1.0, v124
	v_add_f32_e32 v125, 1.0, v125
	v_rcp_f32_e32 v126, v126
	v_rcp_f32_e32 v116, v116
	v_rcp_f32_e32 v118, v118
	v_rcp_f32_e32 v119, v119
	v_rcp_f32_e32 v122, v122
	v_rcp_f32_e32 v123, v123
	v_rcp_f32_e32 v124, v124
	v_rcp_f32_e32 v125, v125
	v_mul_f32_e32 v99, v99, v126
	v_mul_f32_e32 v113, v113, v116
	v_mul_f32_e32 v101, v101, v118
	v_mul_f32_e32 v109, v109, v119
	v_mul_f32_e32 v103, v103, v122
	v_mul_f32_e32 v111, v111, v123
	v_mul_f32_e32 v97, v97, v124
	v_mul_f32_e32 v105, v105, v125
	v_mul_f32_e32 v99, v98, v99
	v_mul_f32_e32 v112, v112, v113
	v_mul_f32_e32 v100, v100, v101
	v_mul_f32_e32 v101, v108, v109
	v_mul_f32_e32 v102, v102, v103
	v_mul_f32_e32 v103, v110, v111
	v_mul_f32_e32 v108, v96, v97
	v_mul_f32_e32 v104, v104, v105
	v_cvt_pk_bf16_f32 v96, v112, v100
	v_cvt_pk_bf16_f32 v97, v101, v102
	v_cvt_pk_bf16_f32 v98, v103, v108
	v_cvt_pk_bf16_f32 v99, v104, v99
	global_store_dwordx4 v[114:115], v[96:99], off
	s_nop 1
	v_mov_b32_e32 v98, v241
	v_add_u32_e32 v101, 48, v151
	v_mov_b32_e32 v97, v84
	v_mov_b32_e32 v84, v93
	v_mov_b32_e32 v93, v86
	v_mov_b32_e32 v86, v95
	v_mov_b32_e32 v95, v80
	v_mov_b32_e32 v80, v89
	v_mov_b32_e32 v89, v82
	v_mov_b32_e32 v82, v91
	v_mov_b32_e32 v96, v92
	v_mov_b32_e32 v92, v94
	v_mov_b32_e32 v94, v88
	v_mov_b32_e32 v88, v90
	v_add_u32_e32 v90, s4, v101
	v_ashrrev_i32_e32 v91, 31, v90
	v_lshl_add_u64 v[90:91], v[90:91], 2, s[14:15]
	v_fmamk_f32 v98, v98, 0x3a800000, v150
	v_mul_f32_e32 v99, 0x4b800000, v98
	v_cmp_gt_f32_e32 vcc, s58, v98
	s_nop 1
	v_cndmask_b32_e32 v98, v98, v99, vcc
	v_rsq_f32_e32 v100, v98
	v_mad_i64_i32 v[98:99], s[30:31], v117, s59, v[120:121]
	v_mul_f32_e32 v102, 0x45800000, v100
	v_cndmask_b32_e32 v100, v100, v102, vcc
	v_pk_mul_f32 v[82:83], v[82:83], v[100:101] op_sel_hi:[1,0]
	v_pk_mul_f32 v[96:97], v[96:97], v[100:101] op_sel_hi:[1,0]
	v_pk_mul_f32 v[84:85], v[84:85], v[100:101] op_sel_hi:[1,0]
	v_pk_mul_f32 v[92:93], v[92:93], v[100:101] op_sel_hi:[1,0]
	v_pk_mul_f32 v[86:87], v[86:87], v[100:101] op_sel_hi:[1,0]
	v_pk_mul_f32 v[94:95], v[94:95], v[100:101] op_sel_hi:[1,0]
	v_pk_mul_f32 v[80:81], v[80:81], v[100:101] op_sel_hi:[1,0]
	v_pk_mul_f32 v[88:89], v[88:89], v[100:101] op_sel_hi:[1,0]
	v_mul_f32_e32 v108, 0xbfb8aa3b, v83
	v_mul_f32_e32 v100, 0xbfb8aa3b, v97
	v_mul_f32_e32 v102, 0xbfb8aa3b, v85
	v_mul_f32_e32 v103, 0xbfb8aa3b, v93
	v_mul_f32_e32 v104, 0xbfb8aa3b, v87
	v_mul_f32_e32 v105, 0xbfb8aa3b, v95
	v_mul_f32_e32 v106, 0xbfb8aa3b, v81
	v_mul_f32_e32 v107, 0xbfb8aa3b, v89
	v_exp_f32_e32 v108, v108
	v_exp_f32_e32 v100, v100
	v_exp_f32_e32 v102, v102
	v_exp_f32_e32 v103, v103
	v_exp_f32_e32 v104, v104
	v_exp_f32_e32 v105, v105
	v_exp_f32_e32 v106, v106
	v_exp_f32_e32 v107, v107
	v_add_f32_e32 v108, 1.0, v108
	v_add_f32_e32 v100, 1.0, v100
	v_add_f32_e32 v102, 1.0, v102
	v_add_f32_e32 v103, 1.0, v103
	v_add_f32_e32 v104, 1.0, v104
	v_add_f32_e32 v105, 1.0, v105
	v_add_f32_e32 v106, 1.0, v106
	v_add_f32_e32 v107, 1.0, v107
	v_rcp_f32_e32 v108, v108
	v_rcp_f32_e32 v100, v100
	v_rcp_f32_e32 v102, v102
	v_rcp_f32_e32 v103, v103
	v_rcp_f32_e32 v104, v104
	v_rcp_f32_e32 v105, v105
	v_rcp_f32_e32 v106, v106
	v_rcp_f32_e32 v107, v107
	v_mul_f32_e32 v83, v83, v108
	v_mul_f32_e32 v97, v97, v100
	v_mul_f32_e32 v85, v85, v102
	v_mul_f32_e32 v93, v93, v103
	v_mul_f32_e32 v87, v87, v104
	v_mul_f32_e32 v95, v95, v105
	v_mul_f32_e32 v81, v81, v106
	v_mul_f32_e32 v89, v89, v107
	v_mul_f32_e32 v83, v82, v83
	v_mul_f32_e32 v96, v96, v97
	v_mul_f32_e32 v84, v84, v85
	v_mul_f32_e32 v85, v92, v93
	v_mul_f32_e32 v86, v86, v87
	v_mul_f32_e32 v87, v94, v95
	v_mul_f32_e32 v92, v80, v81
	v_mul_f32_e32 v88, v88, v89
	v_cvt_pk_bf16_f32 v80, v96, v84
	v_cvt_pk_bf16_f32 v81, v85, v86
	v_cvt_pk_bf16_f32 v82, v87, v92
	v_cvt_pk_bf16_f32 v83, v88, v83
	global_store_dwordx4 v[98:99], v[80:83], off
	s_nop 1
	v_mov_b32_e32 v82, v242
	v_add_u32_e32 v85, 0x80, v151
	v_mov_b32_e32 v81, v68
	v_mov_b32_e32 v68, v77
	v_mov_b32_e32 v77, v70
	v_mov_b32_e32 v70, v79
	v_mov_b32_e32 v79, v64
	v_mov_b32_e32 v64, v73
	v_mov_b32_e32 v73, v66
	v_mov_b32_e32 v66, v75
	v_mov_b32_e32 v80, v76
	v_mov_b32_e32 v76, v78
	v_mov_b32_e32 v78, v72
	v_mov_b32_e32 v72, v74
	v_add_u32_e32 v74, s4, v85
	v_ashrrev_i32_e32 v75, 31, v74
	v_lshl_add_u64 v[74:75], v[74:75], 2, s[14:15]
	v_fmamk_f32 v82, v82, 0x3a800000, v150
	v_mul_f32_e32 v83, 0x4b800000, v82
	v_cmp_gt_f32_e32 vcc, s58, v82
	s_nop 1
	v_cndmask_b32_e32 v82, v82, v83, vcc
	v_rsq_f32_e32 v84, v82
	v_mad_i64_i32 v[82:83], s[30:31], v101, s59, v[120:121]
	v_mul_f32_e32 v86, 0x45800000, v84
	v_cndmask_b32_e32 v84, v84, v86, vcc
	v_pk_mul_f32 v[66:67], v[66:67], v[84:85] op_sel_hi:[1,0]
	v_pk_mul_f32 v[80:81], v[80:81], v[84:85] op_sel_hi:[1,0]
; __device__ __forceinline__ void st8(bf16_t* p, f32x4 a, f32x4 b) { u32x4 w; w.x = cvt_pk_bf16(a[0], a[1]); w.y = cvt_pk_bf16(a[2], a[3]); w.z = cvt_pk_bf16(b[0], b[1]); w.w = cvt_pk_bf16(b[2], b[3]); *(u32x4*)p = w; }
;     __device__ __forceinline__ void operator()(const f32x4 (&acc)[2][2][4][2], const Unit& u, int wr, int wc, int fr, int fq) const {
;     ...
;                 const int rl = rl0 + ai * HALF + m * 16;
;                 const float s = rsqrtf(ssqX[u.pm * BM + rl] * (1.0f / 1024.0f) + EPS);
;                 f32x4 o[2];
; #pragma unroll
;                 for (int n = 0; n < 2; ++n) {
;                     const f32x4 g = acc[ai][0][m][n] * s, up = acc[ai][1][m][n] * s;
; #pragma unroll
;                     for (int j = 0; j < 4; ++j) { const float e = __builtin_amdgcn_exp2f(g[j] * -1.4426950408889634f); o[n][j] = g[j] * __builtin_amdgcn_rcpf(1.0f + e) * up[j]; }
;                 }
;                 st8(base + (size_t)rl * 2816 + pn * 128 + cw, o[0], o[1]);
;                 asm volatile("" ::: "memory");
	v_pk_mul_f32 v[68:69], v[68:69], v[84:85] op_sel_hi:[1,0]
	v_pk_mul_f32 v[76:77], v[76:77], v[84:85] op_sel_hi:[1,0]
	v_pk_mul_f32 v[70:71], v[70:71], v[84:85] op_sel_hi:[1,0]
	v_pk_mul_f32 v[78:79], v[78:79], v[84:85] op_sel_hi:[1,0]
	v_pk_mul_f32 v[64:65], v[64:65], v[84:85] op_sel_hi:[1,0]
	v_pk_mul_f32 v[72:73], v[72:73], v[84:85] op_sel_hi:[1,0]
	v_mul_f32_e32 v92, 0xbfb8aa3b, v67
	v_mul_f32_e32 v84, 0xbfb8aa3b, v81
	v_mul_f32_e32 v86, 0xbfb8aa3b, v69
	v_mul_f32_e32 v87, 0xbfb8aa3b, v77
	v_mul_f32_e32 v88, 0xbfb8aa3b, v71
	v_mul_f32_e32 v89, 0xbfb8aa3b, v79
	v_mul_f32_e32 v90, 0xbfb8aa3b, v65
	v_mul_f32_e32 v91, 0xbfb8aa3b, v73
	v_exp_f32_e32 v92, v92
	v_exp_f32_e32 v84, v84
	v_exp_f32_e32 v86, v86
	v_exp_f32_e32 v87, v87
	v_exp_f32_e32 v88, v88
	v_exp_f32_e32 v89, v89
	v_exp_f32_e32 v90, v90
	v_exp_f32_e32 v91, v91
	v_add_f32_e32 v92, 1.0, v92
	v_add_f32_e32 v84, 1.0, v84
	v_add_f32_e32 v86, 1.0, v86
	v_add_f32_e32 v87, 1.0, v87
	v_add_f32_e32 v88, 1.0, v88
	v_add_f32_e32 v89, 1.0, v89
	v_add_f32_e32 v90, 1.0, v90
	v_add_f32_e32 v91, 1.0, v91
	v_rcp_f32_e32 v92, v92
	v_rcp_f32_e32 v84, v84
	v_rcp_f32_e32 v86, v86
	v_rcp_f32_e32 v87, v87
	v_rcp_f32_e32 v88, v88
	v_rcp_f32_e32 v89, v89
	v_rcp_f32_e32 v90, v90
	v_rcp_f32_e32 v91, v91
	v_mul_f32_e32 v67, v67, v92
	v_mul_f32_e32 v81, v81, v84
	v_mul_f32_e32 v69, v69, v86
	v_mul_f32_e32 v77, v77, v87
	v_mul_f32_e32 v71, v71, v88
	v_mul_f32_e32 v79, v79, v89
	v_mul_f32_e32 v65, v65, v90
	v_mul_f32_e32 v73, v73, v91
	v_mul_f32_e32 v67, v66, v67
	v_mul_f32_e32 v80, v80, v81
	v_mul_f32_e32 v68, v68, v69
	v_mul_f32_e32 v69, v76, v77
	v_mul_f32_e32 v70, v70, v71
	v_mul_f32_e32 v71, v78, v79
	v_mul_f32_e32 v76, v64, v65
	v_mul_f32_e32 v72, v72, v73
	v_cvt_pk_bf16_f32 v64, v80, v68
	v_cvt_pk_bf16_f32 v65, v69, v70
	v_cvt_pk_bf16_f32 v66, v71, v76
	v_cvt_pk_bf16_f32 v67, v72, v67
	global_store_dwordx4 v[82:83], v[64:67], off
	s_nop 1
	v_mov_b32_e32 v66, v243
	v_add_u32_e32 v69, 0x90, v151
	v_mov_b32_e32 v65, v52
	v_mov_b32_e32 v52, v61
	v_mov_b32_e32 v61, v54
	v_mov_b32_e32 v54, v63
	v_mov_b32_e32 v63, v48
	v_mov_b32_e32 v48, v57
	v_mov_b32_e32 v57, v50
	v_mov_b32_e32 v50, v59
	v_mov_b32_e32 v64, v60
	v_mov_b32_e32 v60, v62
	v_mov_b32_e32 v62, v56
	v_mov_b32_e32 v56, v58
	v_add_u32_e32 v58, s4, v69
	v_ashrrev_i32_e32 v59, 31, v58
	v_lshl_add_u64 v[58:59], v[58:59], 2, s[14:15]
	v_fmamk_f32 v66, v66, 0x3a800000, v150
	v_mul_f32_e32 v67, 0x4b800000, v66
	v_cmp_gt_f32_e32 vcc, s58, v66
	s_nop 1
	v_cndmask_b32_e32 v66, v66, v67, vcc
	v_rsq_f32_e32 v68, v66
	v_mad_i64_i32 v[66:67], s[30:31], v85, s59, v[120:121]
	v_mul_f32_e32 v70, 0x45800000, v68
	v_cndmask_b32_e32 v68, v68, v70, vcc
	v_pk_mul_f32 v[50:51], v[50:51], v[68:69] op_sel_hi:[1,0]
	v_pk_mul_f32 v[64:65], v[64:65], v[68:69] op_sel_hi:[1,0]
	v_pk_mul_f32 v[52:53], v[52:53], v[68:69] op_sel_hi:[1,0]
	v_pk_mul_f32 v[60:61], v[60:61], v[68:69] op_sel_hi:[1,0]
	v_pk_mul_f32 v[54:55], v[54:55], v[68:69] op_sel_hi:[1,0]
	v_pk_mul_f32 v[62:63], v[62:63], v[68:69] op_sel_hi:[1,0]
	v_pk_mul_f32 v[48:49], v[48:49], v[68:69] op_sel_hi:[1,0]
	v_pk_mul_f32 v[56:57], v[56:57], v[68:69] op_sel_hi:[1,0]
	v_mul_f32_e32 v76, 0xbfb8aa3b, v51
	v_mul_f32_e32 v68, 0xbfb8aa3b, v65
	v_mul_f32_e32 v70, 0xbfb8aa3b, v53
	v_mul_f32_e32 v71, 0xbfb8aa3b, v61
	v_mul_f32_e32 v72, 0xbfb8aa3b, v55
	v_mul_f32_e32 v73, 0xbfb8aa3b, v63
	v_mul_f32_e32 v74, 0xbfb8aa3b, v49
	v_mul_f32_e32 v75, 0xbfb8aa3b, v57
	v_exp_f32_e32 v76, v76
	v_exp_f32_e32 v68, v68
	v_exp_f32_e32 v70, v70
	v_exp_f32_e32 v71, v71
	v_exp_f32_e32 v72, v72
	v_exp_f32_e32 v73, v73
	v_exp_f32_e32 v74, v74
	v_exp_f32_e32 v75, v75
	v_add_f32_e32 v76, 1.0, v76
	v_add_f32_e32 v68, 1.0, v68
	v_add_f32_e32 v70, 1.0, v70
	v_add_f32_e32 v71, 1.0, v71
	v_add_f32_e32 v72, 1.0, v72
	v_add_f32_e32 v73, 1.0, v73
	v_add_f32_e32 v74, 1.0, v74
	v_add_f32_e32 v75, 1.0, v75
	v_rcp_f32_e32 v76, v76
	v_rcp_f32_e32 v68, v68
	v_rcp_f32_e32 v70, v70
	v_rcp_f32_e32 v71, v71
	v_rcp_f32_e32 v72, v72
	v_rcp_f32_e32 v73, v73
	v_rcp_f32_e32 v74, v74
	v_rcp_f32_e32 v75, v75
	v_mul_f32_e32 v51, v51, v76
	v_mul_f32_e32 v65, v65, v68
	v_mul_f32_e32 v53, v53, v70
	v_mul_f32_e32 v61, v61, v71
	v_mul_f32_e32 v55, v55, v72
	v_mul_f32_e32 v63, v63, v73
	v_mul_f32_e32 v49, v49, v74
	v_mul_f32_e32 v57, v57, v75
	v_mul_f32_e32 v51, v50, v51
	v_mul_f32_e32 v64, v64, v65
	v_mul_f32_e32 v52, v52, v53
	v_mul_f32_e32 v53, v60, v61
	v_mul_f32_e32 v54, v54, v55
	v_mul_f32_e32 v55, v62, v63
	v_mul_f32_e32 v60, v48, v49
	v_mul_f32_e32 v56, v56, v57
	v_cvt_pk_bf16_f32 v48, v64, v52
	v_cvt_pk_bf16_f32 v49, v53, v54
	v_cvt_pk_bf16_f32 v50, v55, v60
	v_cvt_pk_bf16_f32 v51, v56, v51
	global_store_dwordx4 v[66:67], v[48:51], off
	s_nop 1
	v_mov_b32_e32 v50, v244
	v_add_u32_e32 v53, 0xa0, v151
	v_mov_b32_e32 v49, v36
	v_mov_b32_e32 v36, v45
	v_mov_b32_e32 v45, v38
	v_mov_b32_e32 v38, v47
	v_mov_b32_e32 v47, v32
	v_mov_b32_e32 v32, v41
	v_mov_b32_e32 v41, v34
	v_mov_b32_e32 v34, v43
	v_mov_b32_e32 v48, v44
	v_mov_b32_e32 v44, v46
	v_mov_b32_e32 v46, v40
	v_mov_b32_e32 v40, v42
	v_add_u32_e32 v42, s4, v53
	v_ashrrev_i32_e32 v43, 31, v42
	v_lshl_add_u64 v[42:43], v[42:43], 2, s[14:15]
	v_fmamk_f32 v50, v50, 0x3a800000, v150
	v_mul_f32_e32 v51, 0x4b800000, v50
	v_cmp_gt_f32_e32 vcc, s58, v50
	s_nop 1
	v_cndmask_b32_e32 v50, v50, v51, vcc
	v_rsq_f32_e32 v52, v50
	v_mad_i64_i32 v[50:51], s[30:31], v69, s59, v[120:121]
	v_mul_f32_e32 v54, 0x45800000, v52
	v_cndmask_b32_e32 v52, v52, v54, vcc
	v_pk_mul_f32 v[34:35], v[34:35], v[52:53] op_sel_hi:[1,0]
	v_pk_mul_f32 v[48:49], v[48:49], v[52:53] op_sel_hi:[1,0]
	v_pk_mul_f32 v[36:37], v[36:37], v[52:53] op_sel_hi:[1,0]
; __device__ __forceinline__ void st8(bf16_t* p, f32x4 a, f32x4 b) { u32x4 w; w.x = cvt_pk_bf16(a[0], a[1]); w.y = cvt_pk_bf16(a[2], a[3]); w.z = cvt_pk_bf16(b[0], b[1]); w.w = cvt_pk_bf16(b[2], b[3]); *(u32x4*)p = w; }
;     __device__ __forceinline__ void operator()(const f32x4 (&acc)[2][2][4][2], const Unit& u, int wr, int wc, int fr, int fq) const {
;     ...
;                 const int rl = rl0 + ai * HALF + m * 16;
;                 const float s = rsqrtf(ssqX[u.pm * BM + rl] * (1.0f / 1024.0f) + EPS);
;                 f32x4 o[2];
; #pragma unroll
;                 for (int n = 0; n < 2; ++n) {
;                     const f32x4 g = acc[ai][0][m][n] * s, up = acc[ai][1][m][n] * s;
; #pragma unroll
;                     for (int j = 0; j < 4; ++j) { const float e = __builtin_amdgcn_exp2f(g[j] * -1.4426950408889634f); o[n][j] = g[j] * __builtin_amdgcn_rcpf(1.0f + e) * up[j]; }
;                 }
;                 st8(base + (size_t)rl * 2816 + pn * 128 + cw, o[0], o[1]);
;                 asm volatile("" ::: "memory");
	v_pk_mul_f32 v[44:45], v[44:45], v[52:53] op_sel_hi:[1,0]
	v_pk_mul_f32 v[38:39], v[38:39], v[52:53] op_sel_hi:[1,0]
	v_pk_mul_f32 v[46:47], v[46:47], v[52:53] op_sel_hi:[1,0]
	v_pk_mul_f32 v[32:33], v[32:33], v[52:53] op_sel_hi:[1,0]
	v_pk_mul_f32 v[40:41], v[40:41], v[52:53] op_sel_hi:[1,0]
	v_mul_f32_e32 v60, 0xbfb8aa3b, v35
	v_mul_f32_e32 v52, 0xbfb8aa3b, v49
	v_mul_f32_e32 v54, 0xbfb8aa3b, v37
	v_mul_f32_e32 v55, 0xbfb8aa3b, v45
	v_mul_f32_e32 v56, 0xbfb8aa3b, v39
	v_mul_f32_e32 v57, 0xbfb8aa3b, v47
	v_mul_f32_e32 v58, 0xbfb8aa3b, v33
	v_mul_f32_e32 v59, 0xbfb8aa3b, v41
	v_exp_f32_e32 v60, v60
	v_exp_f32_e32 v52, v52
	v_exp_f32_e32 v54, v54
	v_exp_f32_e32 v55, v55
	v_exp_f32_e32 v56, v56
	v_exp_f32_e32 v57, v57
	v_exp_f32_e32 v58, v58
	v_exp_f32_e32 v59, v59
	v_add_f32_e32 v60, 1.0, v60
	v_add_f32_e32 v52, 1.0, v52
	v_add_f32_e32 v54, 1.0, v54
	v_add_f32_e32 v55, 1.0, v55
	v_add_f32_e32 v56, 1.0, v56
	v_add_f32_e32 v57, 1.0, v57
	v_add_f32_e32 v58, 1.0, v58
	v_add_f32_e32 v59, 1.0, v59
	v_rcp_f32_e32 v60, v60
	v_rcp_f32_e32 v52, v52
	v_rcp_f32_e32 v54, v54
	v_rcp_f32_e32 v55, v55
	v_rcp_f32_e32 v56, v56
	v_rcp_f32_e32 v57, v57
	v_rcp_f32_e32 v58, v58
	v_rcp_f32_e32 v59, v59
	v_mul_f32_e32 v35, v35, v60
	v_mul_f32_e32 v49, v49, v52
	v_mul_f32_e32 v37, v37, v54
	v_mul_f32_e32 v45, v45, v55
	v_mul_f32_e32 v39, v39, v56
	v_mul_f32_e32 v47, v47, v57
	v_mul_f32_e32 v33, v33, v58
	v_mul_f32_e32 v41, v41, v59
	v_mul_f32_e32 v35, v34, v35
	v_mul_f32_e32 v48, v48, v49
	v_mul_f32_e32 v36, v36, v37
	v_mul_f32_e32 v37, v44, v45
	v_mul_f32_e32 v38, v38, v39
	v_mul_f32_e32 v39, v46, v47
	v_mul_f32_e32 v44, v32, v33
	v_mul_f32_e32 v40, v40, v41
	v_cvt_pk_bf16_f32 v32, v48, v36
	v_cvt_pk_bf16_f32 v33, v37, v38
	v_cvt_pk_bf16_f32 v34, v39, v44
	v_cvt_pk_bf16_f32 v35, v40, v35
	global_store_dwordx4 v[50:51], v[32:35], off
	s_nop 1
	v_mov_b32_e32 v34, v245
	v_add_u32_e32 v37, 0xb0, v151
	v_mov_b32_e32 v33, v20
	v_mov_b32_e32 v20, v29
	v_mov_b32_e32 v29, v22
	v_mov_b32_e32 v22, v31
	v_mov_b32_e32 v31, v16
	v_mov_b32_e32 v16, v25
	v_mov_b32_e32 v25, v18
	v_mov_b32_e32 v18, v27
	v_mov_b32_e32 v32, v28
	v_mov_b32_e32 v28, v30
	v_mov_b32_e32 v30, v24
	v_mov_b32_e32 v24, v26
	v_add_u32_e32 v26, s4, v37
	v_ashrrev_i32_e32 v27, 31, v26
	v_lshl_add_u64 v[26:27], v[26:27], 2, s[14:15]
	v_fmamk_f32 v34, v34, 0x3a800000, v150
	v_mul_f32_e32 v35, 0x4b800000, v34
	v_cmp_gt_f32_e32 vcc, s58, v34
	s_nop 1
	v_cndmask_b32_e32 v34, v34, v35, vcc
	v_rsq_f32_e32 v36, v34
	v_mad_i64_i32 v[34:35], s[4:5], v53, s59, v[120:121]
	v_mul_f32_e32 v38, 0x45800000, v36
	v_cndmask_b32_e32 v36, v36, v38, vcc
	v_pk_mul_f32 v[18:19], v[18:19], v[36:37] op_sel_hi:[1,0]
	v_pk_mul_f32 v[32:33], v[32:33], v[36:37] op_sel_hi:[1,0]
	v_pk_mul_f32 v[20:21], v[20:21], v[36:37] op_sel_hi:[1,0]
	v_pk_mul_f32 v[28:29], v[28:29], v[36:37] op_sel_hi:[1,0]
	v_pk_mul_f32 v[22:23], v[22:23], v[36:37] op_sel_hi:[1,0]
	v_pk_mul_f32 v[30:31], v[30:31], v[36:37] op_sel_hi:[1,0]
	v_pk_mul_f32 v[16:17], v[16:17], v[36:37] op_sel_hi:[1,0]
	v_pk_mul_f32 v[24:25], v[24:25], v[36:37] op_sel_hi:[1,0]
	v_mul_f32_e32 v44, 0xbfb8aa3b, v19
	v_mul_f32_e32 v36, 0xbfb8aa3b, v33
	v_mul_f32_e32 v38, 0xbfb8aa3b, v21
	v_mul_f32_e32 v39, 0xbfb8aa3b, v29
	v_mul_f32_e32 v40, 0xbfb8aa3b, v23
	v_mul_f32_e32 v41, 0xbfb8aa3b, v31
	v_mul_f32_e32 v42, 0xbfb8aa3b, v17
	v_mul_f32_e32 v43, 0xbfb8aa3b, v25
	v_exp_f32_e32 v44, v44
	v_exp_f32_e32 v36, v36
	v_exp_f32_e32 v38, v38
	v_exp_f32_e32 v39, v39
	v_exp_f32_e32 v40, v40
	v_exp_f32_e32 v41, v41
	v_exp_f32_e32 v42, v42
	v_exp_f32_e32 v43, v43
	v_add_f32_e32 v44, 1.0, v44
	v_add_f32_e32 v36, 1.0, v36
	v_add_f32_e32 v38, 1.0, v38
	v_add_f32_e32 v39, 1.0, v39
	v_add_f32_e32 v40, 1.0, v40
	v_add_f32_e32 v41, 1.0, v41
	v_add_f32_e32 v42, 1.0, v42
	v_add_f32_e32 v43, 1.0, v43
	v_rcp_f32_e32 v44, v44
	v_rcp_f32_e32 v36, v36
	v_rcp_f32_e32 v38, v38
	v_rcp_f32_e32 v39, v39
	v_rcp_f32_e32 v40, v40
	v_rcp_f32_e32 v41, v41
	v_rcp_f32_e32 v42, v42
	v_rcp_f32_e32 v43, v43
	v_mul_f32_e32 v19, v19, v44
	v_mul_f32_e32 v33, v33, v36
	v_mul_f32_e32 v21, v21, v38
	v_mul_f32_e32 v29, v29, v39
	v_mul_f32_e32 v23, v23, v40
	v_mul_f32_e32 v31, v31, v41
	v_mul_f32_e32 v17, v17, v42
	v_mul_f32_e32 v25, v25, v43
	v_mul_f32_e32 v19, v18, v19
	v_mul_f32_e32 v32, v32, v33
	v_mul_f32_e32 v20, v20, v21
	v_mul_f32_e32 v21, v28, v29
	v_mul_f32_e32 v22, v22, v23
	v_mul_f32_e32 v23, v30, v31
	v_mul_f32_e32 v28, v16, v17
	v_mul_f32_e32 v24, v24, v25
	v_cvt_pk_bf16_f32 v16, v32, v20
	v_cvt_pk_bf16_f32 v17, v21, v22
	v_cvt_pk_bf16_f32 v18, v23, v28
	v_cvt_pk_bf16_f32 v19, v24, v19
	global_store_dwordx4 v[34:35], v[16:19], off
	s_nop 1
	v_mov_b32_e32 v18, v246
	s_nop 0
	v_mov_b32_e32 v17, v4
	v_mov_b32_e32 v4, v13
	v_mov_b32_e32 v13, v6
	v_mov_b32_e32 v6, v15
	v_mov_b32_e32 v15, v0
	v_mov_b32_e32 v0, v9
	v_mov_b32_e32 v9, v2
	v_mov_b32_e32 v16, v12
	v_mov_b32_e32 v12, v14
	v_mov_b32_e32 v14, v8
	v_mov_b32_e32 v8, v10
	s_waitcnt vmcnt(0)
; __device__ __forceinline__ void st8(bf16_t* p, f32x4 a, f32x4 b) { u32x4 w; w.x = cvt_pk_bf16(a[0], a[1]); w.y = cvt_pk_bf16(a[2], a[3]); w.z = cvt_pk_bf16(b[0], b[1]); w.w = cvt_pk_bf16(b[2], b[3]); *(u32x4*)p = w; }
; #define PG8_BAR __builtin_amdgcn_s_barrier()
;     __device__ __forceinline__ void operator()(const f32x4 (&acc)[2][2][4][2], const Unit& u, int wr, int wc, int fr, int fq) const {
;     ...
;                 const int rl = rl0 + ai * HALF + m * 16;
;                 const float s = rsqrtf(ssqX[u.pm * BM + rl] * (1.0f / 1024.0f) + EPS);
;                 f32x4 o[2];
; #pragma unroll
;                 for (int n = 0; n < 2; ++n) {
;                     const f32x4 g = acc[ai][0][m][n] * s, up = acc[ai][1][m][n] * s;
; #pragma unroll
;                     for (int j = 0; j < 4; ++j) { const float e = __builtin_amdgcn_exp2f(g[j] * -1.4426950408889634f); o[n][j] = g[j] * __builtin_amdgcn_rcpf(1.0f + e) * up[j]; }
;                 }
;                 st8(base + (size_t)rl * 2816 + pn * 128 + cw, o[0], o[1]);
;                 asm volatile("" ::: "memory");
; template <class Epi, class Sched, bool ALIGN_EPI = false, bool SP2 = false>
; __device__ __forceinline__ void gemm_phase(PG8_LAS unsigned char* lds, const Gemm g, const Sched& S, const Epi& E) {
;     ...
;         if constexpr (!Epi::AFTER_DRAIN) { E(acc, cur, wr, wc, fr, fq); S.done(cur); }
;         if (!has_next) break;
; #pragma unroll
;         for (int a = 0; a < 2; ++a)
; #pragma unroll
;             for (int b = 0; b < 2; ++b)
; #pragma unroll
;                 for (int m = 0; m < 4; ++m)
; #pragma unroll
;                     for (int n = 0; n < 2; ++n) acc[a][b][m][n] = (f32x4){0.f, 0.f, 0.f, 0.f};
;         cur = nxt; cA = nA; cB = nB; ++ui;
;         if constexpr (ALIGN_EPI) { if (wr == 1) PG8_BAR; }
	v_fmamk_f32 v2, v18, 0x3a800000, v150
	v_mul_f32_e32 v10, 0x4b800000, v2
	v_cmp_gt_f32_e32 vcc, s58, v2
	s_nop 1
	v_cndmask_b32_e32 v2, v2, v10, vcc
	v_rsq_f32_e32 v18, v2
	v_mov_b32_e32 v2, v11
	v_mad_i64_i32 v[10:11], s[4:5], v37, s59, v[120:121]
	v_mul_f32_e32 v19, 0x45800000, v18
	v_cndmask_b32_e32 v18, v18, v19, vcc
	v_pk_mul_f32 v[2:3], v[2:3], v[18:19] op_sel_hi:[1,0]
	v_pk_mul_f32 v[16:17], v[16:17], v[18:19] op_sel_hi:[1,0]
	v_pk_mul_f32 v[4:5], v[4:5], v[18:19] op_sel_hi:[1,0]
	v_pk_mul_f32 v[12:13], v[12:13], v[18:19] op_sel_hi:[1,0]
	v_pk_mul_f32 v[6:7], v[6:7], v[18:19] op_sel_hi:[1,0]
	v_pk_mul_f32 v[14:15], v[14:15], v[18:19] op_sel_hi:[1,0]
	v_pk_mul_f32 v[0:1], v[0:1], v[18:19] op_sel_hi:[1,0]
	v_pk_mul_f32 v[8:9], v[8:9], v[18:19] op_sel_hi:[1,0]
	v_mul_f32_e32 v25, 0xbfb8aa3b, v3
	v_mul_f32_e32 v18, 0xbfb8aa3b, v17
	v_mul_f32_e32 v19, 0xbfb8aa3b, v5
	v_mul_f32_e32 v20, 0xbfb8aa3b, v13
	v_mul_f32_e32 v21, 0xbfb8aa3b, v7
	v_mul_f32_e32 v22, 0xbfb8aa3b, v15
	v_mul_f32_e32 v23, 0xbfb8aa3b, v1
	v_mul_f32_e32 v24, 0xbfb8aa3b, v9
	v_exp_f32_e32 v25, v25
	v_exp_f32_e32 v18, v18
	v_exp_f32_e32 v19, v19
	v_exp_f32_e32 v20, v20
	v_exp_f32_e32 v21, v21
	v_exp_f32_e32 v22, v22
	v_exp_f32_e32 v23, v23
	v_exp_f32_e32 v24, v24
	v_add_f32_e32 v25, 1.0, v25
	v_add_f32_e32 v18, 1.0, v18
	v_add_f32_e32 v19, 1.0, v19
	v_add_f32_e32 v20, 1.0, v20
	v_add_f32_e32 v21, 1.0, v21
	v_add_f32_e32 v22, 1.0, v22
	v_add_f32_e32 v23, 1.0, v23
	v_add_f32_e32 v24, 1.0, v24
	v_rcp_f32_e32 v25, v25
	v_rcp_f32_e32 v18, v18
	v_rcp_f32_e32 v19, v19
	v_rcp_f32_e32 v20, v20
	v_rcp_f32_e32 v21, v21
	v_rcp_f32_e32 v22, v22
	v_rcp_f32_e32 v23, v23
	v_rcp_f32_e32 v24, v24
	v_mul_f32_e32 v3, v3, v25
	v_mul_f32_e32 v17, v17, v18
	v_mul_f32_e32 v5, v5, v19
	v_mul_f32_e32 v13, v13, v20
	v_mul_f32_e32 v7, v7, v21
	v_mul_f32_e32 v15, v15, v22
	v_mul_f32_e32 v1, v1, v23
	v_mul_f32_e32 v9, v9, v24
	v_mul_f32_e32 v3, v2, v3
	v_mul_f32_e32 v16, v16, v17
	v_mul_f32_e32 v4, v4, v5
	v_mul_f32_e32 v5, v12, v13
	v_mul_f32_e32 v6, v6, v7
	v_mul_f32_e32 v7, v14, v15
	v_mul_f32_e32 v12, v0, v1
	v_mul_f32_e32 v8, v8, v9
	v_cvt_pk_bf16_f32 v0, v16, v4
	v_cvt_pk_bf16_f32 v1, v5, v6
	v_cvt_pk_bf16_f32 v2, v7, v12
	v_cvt_pk_bf16_f32 v3, v8, v3
	global_store_dwordx4 v[10:11], v[0:3], off
	s_and_b64 vcc, exec, s[2:3]
	s_mov_b64 s[2:3], -1
	s_cbranch_vccnz .LBB0_1601
	s_andn2_b64 vcc, exec, s[12:13]
	s_cbranch_vccnz .LBB0_1600
	s_barrier
	s_branch .LBB0_1600
